# v033 + sc1 on the EpiR ssq atomics
# baseline (speedup 1.0000x reference)
;     __device__ __forceinline__ void operator()(const f32x4 (&acc)[2][2][4][2], const RU& u, int wr, int wc, int fr, int fq) const {
;     ...
;         asm volatile("s_waitcnt lgkmcnt(0)" ::: "memory"); __builtin_amdgcn_s_barrier(); asm volatile("" ::: "memory");
;         { const int t_ = (wr * 4 + wc) * 64 + ln_;
;           if (t_ < 256) atomicAdd(ssq + u.pm * 256 + t_, (u64)__float2ull_rn(((red[t_] + red[256 + t_]) + (red[512 + t_] + red[768 + t_])) * SSQ_SCALE)); }
.LBB0_701:
	s_or_b64 exec, exec, s[16:17]
	s_waitcnt lgkmcnt(0)
	s_barrier
	s_and_saveexec_b64 s[16:17], s[4:5]
	s_cbranch_execz .LBB0_703
	ds_read2st64_b32 v[2:3], v225 offset1:4
	s_lshl_b32 s72, s18, 3
	s_waitcnt lgkmcnt(0)
	v_lshl_add_u64 v[0:1], v[194:195], 0, s[72:73]
	v_add_f32_e32 v4, v2, v3
	ds_read2st64_b32 v[2:3], v225 offset0:8 offset1:12
	s_waitcnt lgkmcnt(0)
	v_add_f32_e32 v2, v2, v3
	v_add_f32_e32 v2, v4, v2
	v_mul_f32_e32 v2, 0x4b800000, v2
	v_rndne_f32_e32 v2, v2
	v_mul_f32_e32 v3, 0x2f800000, v2
	v_floor_f32_e32 v3, v3
	v_fmac_f32_e32 v2, 0xcf800000, v3
	v_cvt_u32_f32_e32 v2, v2
	v_cvt_u32_f32_e32 v3, v3
	flat_atomic_add_x2 v[0:1], v[2:3] sc1
